# P4 epilogue: p@W_pp (PP) loads use nt policy; plus P0/P3 x loads nt
# baseline (speedup 1.0000x reference)
.LBB0_477:
	v_mov_b32_e32 v144, v254
	s_lshl_b32 s21, s26, 8
	v_readfirstlane_b32 s19, v144
	s_ashr_i32 s26, s19, 2
	s_andn2_b32 s26, s26, 63
	s_add_i32 s26, s26, s21
	v_and_or_b32 v142, v144, 15, s26
	v_ashrrev_i32_e32 v143, 31, v142
	v_lshlrev_b64 v[140:141], 6, v[142:143]
	v_lshl_add_u64 v[140:141], s[6:7], 0, v[140:141]
	global_load_dwordx4 v[152:155], v[140:141], off
	global_load_dwordx4 v[156:159], v[140:141], off offset:16
	global_load_dwordx4 v[160:163], v[140:141], off offset:48
	global_load_dwordx4 v[164:167], v[140:141], off offset:32
	s_lshl_b32 s21, s49, 8
	s_and_b32 s19, s19, 0xc0
	v_lshrrev_b32_e32 v144, 1, v144
	s_or_b32 s19, s19, s21
	v_and_or_b32 v140, v144, 24, s19
	v_ashrrev_i32_e32 v141, 31, v140
	v_lshlrev_b64 v[144:145], 10, v[142:143]
	v_lshl_add_u64 v[144:145], v[144:145], 0, v[140:141]
	v_lshlrev_b64 v[172:173], 1, v[144:145]
	v_lshl_add_u64 v[176:177], s[16:17], 0, v[172:173]
	v_lshl_add_u64 v[178:179], s[14:15], 0, v[172:173]
	global_load_dwordx4 v[168:171], v[176:177], off
	global_load_dwordx4 v[172:175], v[178:179], off nt
	v_lshl_add_u64 v[144:145], v[144:145], 2, s[30:31]
	s_waitcnt vmcnt(0)
	v_mov_b32_e32 v180, v153
	v_mov_b32_e32 v181, v154
	v_mov_b32_e32 v153, v155
	v_mov_b32_e32 v154, v157
	v_mov_b32_e32 v155, v158
	v_mov_b32_e32 v157, v159
	v_pk_add_f32 v[152:153], v[180:181], v[152:153]
	v_pk_add_f32 v[154:155], v[154:155], v[156:157]
	v_pk_add_f32 v[152:153], v[152:153], v[152:153] op_sel:[0,1] op_sel_hi:[1,0]
	v_pk_add_f32 v[154:155], v[154:155], v[154:155] op_sel:[0,1] op_sel_hi:[1,0]
	v_add_f32_e32 v158, v164, v165
	v_add_f32_e32 v164, v166, v167
	v_mov_b32_e32 v159, v162
	v_mov_b32_e32 v165, v163
	v_mov_b32_e32 v153, v160
	v_mov_b32_e32 v155, v161
	v_pk_add_f32 v[156:157], v[158:159], v[164:165]
	v_pk_add_f32 v[152:153], v[152:153], v[154:155]
	v_lshlrev_b32_e32 v158, 16, v168
	v_pk_add_f32 v[152:153], v[152:153], v[156:157]
	v_and_b32_e32 v159, 0xffff0000, v168
	v_add_f32_e32 v143, v152, v153
	v_fmamk_f32 v143, v143, 0x3a800000, v150
	v_mul_f32_e32 v151, 0x4b800000, v143
	v_cmp_gt_f32_e32 vcc, s48, v143
	v_lshlrev_b32_e32 v162, 16, v172
	v_and_b32_e32 v163, 0xffff0000, v172
	v_cndmask_b32_e32 v143, v143, v151, vcc
	v_rsq_f32_e32 v143, v143
	v_lshlrev_b32_e32 v164, 16, v169
	v_and_b32_e32 v165, 0xffff0000, v169
	v_lshlrev_b32_e32 v166, 16, v173
	v_mul_f32_e32 v151, 0x45800000, v143
	v_cndmask_b32_e32 v154, v143, v151, vcc
	v_pk_mul_f32 v[126:127], v[126:127], v[154:155] op_sel_hi:[1,0]
	v_pk_mul_f32 v[124:125], v[124:125], v[154:155] op_sel_hi:[1,0]
	v_pk_mul_f32 v[122:123], v[122:123], v[154:155] op_sel_hi:[1,0]
	v_pk_mul_f32 v[120:121], v[120:121], v[154:155] op_sel_hi:[1,0]
	v_mul_f32_e32 v124, 0xbfb8aa3b, v124
	v_mul_f32_e32 v125, 0xbfb8aa3b, v125
	v_mul_f32_e32 v126, 0xbfb8aa3b, v126
	v_mul_f32_e32 v127, 0xbfb8aa3b, v127
	v_mul_f32_e32 v120, 0xbfb8aa3b, v120
	v_mul_f32_e32 v121, 0xbfb8aa3b, v121
	v_mul_f32_e32 v122, 0xbfb8aa3b, v122
	v_mul_f32_e32 v123, 0xbfb8aa3b, v123
	v_exp_f32_e32 v124, v124
	v_exp_f32_e32 v125, v125
	v_exp_f32_e32 v126, v126
	v_exp_f32_e32 v127, v127
	v_exp_f32_e32 v120, v120
	v_exp_f32_e32 v121, v121
	v_exp_f32_e32 v122, v122
	v_exp_f32_e32 v123, v123
	v_add_f32_e32 v124, 1.0, v124
	v_add_f32_e32 v125, 1.0, v125
	v_add_f32_e32 v126, 1.0, v126
	v_add_f32_e32 v127, 1.0, v127
	v_add_f32_e32 v143, 1.0, v120
	v_add_f32_e32 v151, 1.0, v121
	v_add_f32_e32 v155, 1.0, v122
	v_add_f32_e32 v156, 1.0, v123
	v_rcp_f32_e32 v120, v124
	v_rcp_f32_e32 v121, v125
	v_rcp_f32_e32 v122, v126
	v_rcp_f32_e32 v123, v127
	v_rcp_f32_e32 v124, v143
	v_rcp_f32_e32 v125, v151
	v_rcp_f32_e32 v126, v155
	v_rcp_f32_e32 v127, v156
	v_and_b32_e32 v167, 0xffff0000, v173
	v_lshlrev_b32_e32 v168, 16, v170
	v_and_b32_e32 v169, 0xffff0000, v170
	v_lshlrev_b32_e32 v172, 16, v174
	v_and_b32_e32 v173, 0xffff0000, v174
	v_lshlrev_b32_e32 v170, 16, v171
	v_and_b32_e32 v171, 0xffff0000, v171
	v_lshlrev_b32_e32 v152, 16, v175
	v_and_b32_e32 v153, 0xffff0000, v175
	v_pk_fma_f32 v[120:121], v[120:121], v[162:163], v[158:159]
	v_pk_fma_f32 v[122:123], v[122:123], v[166:167], v[164:165]
	v_pk_fma_f32 v[124:125], v[124:125], v[172:173], v[168:169]
	v_pk_fma_f32 v[126:127], v[126:127], v[152:153], v[170:171]
	global_store_dwordx4 v[144:145], v[120:123], off nt
	global_store_dwordx4 v[144:145], v[124:127], off offset:16 nt
	global_load_dwordx4 v[120:123], v[176:177], off offset:64
	s_nop 0
	global_load_dwordx4 v[124:127], v[178:179], off offset:64 nt
	v_pk_mul_f32 v[118:119], v[118:119], v[154:155] op_sel_hi:[1,0]
	v_pk_mul_f32 v[116:117], v[116:117], v[154:155] op_sel_hi:[1,0]
	v_pk_mul_f32 v[114:115], v[114:115], v[154:155] op_sel_hi:[1,0]
	v_pk_mul_f32 v[112:113], v[112:113], v[154:155] op_sel_hi:[1,0]
	v_mul_f32_e32 v116, 0xbfb8aa3b, v116
	v_mul_f32_e32 v117, 0xbfb8aa3b, v117
	v_mul_f32_e32 v118, 0xbfb8aa3b, v118
	v_mul_f32_e32 v119, 0xbfb8aa3b, v119
	v_mul_f32_e32 v112, 0xbfb8aa3b, v112
	v_mul_f32_e32 v113, 0xbfb8aa3b, v113
	v_mul_f32_e32 v114, 0xbfb8aa3b, v114
	v_mul_f32_e32 v115, 0xbfb8aa3b, v115
	v_exp_f32_e32 v116, v116
	v_exp_f32_e32 v117, v117
	v_exp_f32_e32 v118, v118
	v_exp_f32_e32 v119, v119
	v_exp_f32_e32 v112, v112
	v_exp_f32_e32 v113, v113
	v_exp_f32_e32 v114, v114
	v_exp_f32_e32 v115, v115
	v_add_f32_e32 v116, 1.0, v116
	v_add_f32_e32 v117, 1.0, v117
	v_add_f32_e32 v118, 1.0, v118
	v_add_f32_e32 v119, 1.0, v119
	v_add_f32_e32 v143, 1.0, v112
	v_add_f32_e32 v151, 1.0, v113
	v_add_f32_e32 v154, 1.0, v114
	v_add_f32_e32 v155, 1.0, v115
	v_rcp_f32_e32 v112, v116
	v_rcp_f32_e32 v113, v117
	v_rcp_f32_e32 v114, v118
	v_rcp_f32_e32 v115, v119
	v_rcp_f32_e32 v116, v143
	v_rcp_f32_e32 v117, v151
	v_rcp_f32_e32 v118, v154
	v_rcp_f32_e32 v119, v155
	v_or_b32_e32 v152, 16, v142
	v_ashrrev_i32_e32 v153, 31, v152
	v_lshlrev_b64 v[156:157], 6, v[152:153]
	v_lshl_add_u64 v[156:157], s[6:7], 0, v[156:157]
	s_waitcnt vmcnt(1)
	v_lshlrev_b32_e32 v154, 16, v120
	v_and_b32_e32 v155, 0xffff0000, v120
	s_waitcnt vmcnt(0)
	v_lshlrev_b32_e32 v158, 16, v124
	v_and_b32_e32 v159, 0xffff0000, v124
	v_lshlrev_b32_e32 v120, 16, v121
	v_and_b32_e32 v121, 0xffff0000, v121
	v_lshlrev_b32_e32 v124, 16, v125
	v_and_b32_e32 v125, 0xffff0000, v125
	v_lshlrev_b32_e32 v160, 16, v122
	v_and_b32_e32 v161, 0xffff0000, v122
	v_lshlrev_b32_e32 v162, 16, v126
	v_and_b32_e32 v163, 0xffff0000, v126
	v_lshlrev_b32_e32 v122, 16, v123
	v_and_b32_e32 v123, 0xffff0000, v123
	v_lshlrev_b32_e32 v126, 16, v127
	v_and_b32_e32 v127, 0xffff0000, v127
	v_pk_fma_f32 v[112:113], v[112:113], v[158:159], v[154:155]
	v_pk_fma_f32 v[114:115], v[114:115], v[124:125], v[120:121]
	v_pk_fma_f32 v[116:117], v[116:117], v[162:163], v[160:161]
	v_pk_fma_f32 v[118:119], v[118:119], v[126:127], v[122:123]
	global_store_dwordx4 v[144:145], v[112:115], off offset:128 nt
	global_store_dwordx4 v[144:145], v[116:119], off offset:144 nt
	global_load_dwordx4 v[114:117], v[156:157], off
	s_nop 0
	global_load_dwordx4 v[118:121], v[156:157], off offset:16
	v_lshlrev_b64 v[112:113], 10, v[152:153]
	global_load_dwordx4 v[122:125], v[156:157], off offset:48
	global_load_dwordx4 v[152:155], v[156:157], off offset:32
	v_lshl_add_u64 v[112:113], v[112:113], 0, v[140:141]
	v_lshlrev_b64 v[126:127], 1, v[112:113]
	v_lshl_add_u64 v[144:145], s[16:17], 0, v[126:127]
	v_lshl_add_u64 v[126:127], s[14:15], 0, v[126:127]
	global_load_dwordx4 v[156:159], v[144:145], off
	global_load_dwordx4 v[160:163], v[126:127], off nt
	v_lshl_add_u64 v[112:113], v[112:113], 2, s[30:31]
	s_waitcnt vmcnt(5)
	v_mov_b32_e32 v164, v115
	v_mov_b32_e32 v165, v116
	v_mov_b32_e32 v115, v117
	s_waitcnt vmcnt(4)
	v_mov_b32_e32 v116, v119
	v_mov_b32_e32 v117, v120
	v_mov_b32_e32 v119, v121
	v_pk_add_f32 v[114:115], v[164:165], v[114:115]
	v_pk_add_f32 v[116:117], v[116:117], v[118:119]
	v_pk_add_f32 v[114:115], v[114:115], v[114:115] op_sel:[0,1] op_sel_hi:[1,0]
	v_pk_add_f32 v[116:117], v[116:117], v[116:117] op_sel:[0,1] op_sel_hi:[1,0]
	s_waitcnt vmcnt(2)
	v_add_f32_e32 v120, v152, v153
	v_add_f32_e32 v152, v154, v155
	v_mov_b32_e32 v121, v124
	v_mov_b32_e32 v153, v125
	v_mov_b32_e32 v115, v122
	v_mov_b32_e32 v117, v123
	v_pk_add_f32 v[118:119], v[120:121], v[152:153]
	v_pk_add_f32 v[114:115], v[114:115], v[116:117]
	s_waitcnt vmcnt(1)
	v_lshlrev_b32_e32 v124, 16, v156
	v_pk_add_f32 v[114:115], v[114:115], v[118:119]
	v_and_b32_e32 v125, 0xffff0000, v156
	v_add_f32_e32 v114, v114, v115
	v_fmamk_f32 v114, v114, 0x3a800000, v150
	v_mul_f32_e32 v115, 0x4b800000, v114
	v_cmp_gt_f32_e32 vcc, s48, v114
	s_waitcnt vmcnt(0)
	v_lshlrev_b32_e32 v154, 16, v160
	v_and_b32_e32 v155, 0xffff0000, v160
	v_cndmask_b32_e32 v114, v114, v115, vcc
	v_rsq_f32_e32 v116, v114
	v_lshlrev_b32_e32 v156, 16, v157
	v_and_b32_e32 v157, 0xffff0000, v157
	v_lshlrev_b32_e32 v160, 16, v161
	v_mul_f32_e32 v117, 0x45800000, v116
	v_cndmask_b32_e32 v116, v116, v117, vcc
	v_pk_mul_f32 v[110:111], v[110:111], v[116:117] op_sel_hi:[1,0]
	v_pk_mul_f32 v[108:109], v[108:109], v[116:117] op_sel_hi:[1,0]
	v_pk_mul_f32 v[106:107], v[106:107], v[116:117] op_sel_hi:[1,0]
	v_pk_mul_f32 v[104:105], v[104:105], v[116:117] op_sel_hi:[1,0]
	v_mul_f32_e32 v108, 0xbfb8aa3b, v108
	v_mul_f32_e32 v109, 0xbfb8aa3b, v109
	v_mul_f32_e32 v110, 0xbfb8aa3b, v110
	v_mul_f32_e32 v111, 0xbfb8aa3b, v111
	v_mul_f32_e32 v104, 0xbfb8aa3b, v104
	v_mul_f32_e32 v105, 0xbfb8aa3b, v105
	v_mul_f32_e32 v106, 0xbfb8aa3b, v106
	v_mul_f32_e32 v107, 0xbfb8aa3b, v107
	v_exp_f32_e32 v108, v108
	v_exp_f32_e32 v109, v109
	v_exp_f32_e32 v110, v110
	v_exp_f32_e32 v111, v111
	v_exp_f32_e32 v104, v104
	v_exp_f32_e32 v105, v105
	v_exp_f32_e32 v106, v106
	v_exp_f32_e32 v107, v107
	v_add_f32_e32 v108, 1.0, v108
	v_add_f32_e32 v109, 1.0, v109
	v_add_f32_e32 v110, 1.0, v110
	v_add_f32_e32 v111, 1.0, v111
	v_add_f32_e32 v117, 1.0, v104
	v_add_f32_e32 v118, 1.0, v105
	v_add_f32_e32 v119, 1.0, v106
	v_add_f32_e32 v120, 1.0, v107
	v_rcp_f32_e32 v104, v108
	v_rcp_f32_e32 v105, v109
	v_rcp_f32_e32 v106, v110
	v_rcp_f32_e32 v107, v111
	v_rcp_f32_e32 v108, v117
	v_rcp_f32_e32 v109, v118
	v_rcp_f32_e32 v110, v119
	v_rcp_f32_e32 v111, v120
	v_and_b32_e32 v161, 0xffff0000, v161
	v_lshlrev_b32_e32 v166, 16, v158
	v_and_b32_e32 v167, 0xffff0000, v158
	v_lshlrev_b32_e32 v168, 16, v162
	v_and_b32_e32 v169, 0xffff0000, v162
	v_lshlrev_b32_e32 v158, 16, v159
	v_and_b32_e32 v159, 0xffff0000, v159
	v_lshlrev_b32_e32 v114, 16, v163
	v_and_b32_e32 v115, 0xffff0000, v163
	v_pk_fma_f32 v[104:105], v[104:105], v[154:155], v[124:125]
	v_pk_fma_f32 v[106:107], v[106:107], v[160:161], v[156:157]
	v_pk_fma_f32 v[108:109], v[108:109], v[168:169], v[166:167]
	v_pk_fma_f32 v[110:111], v[110:111], v[114:115], v[158:159]
	global_store_dwordx4 v[112:113], v[104:107], off nt
	global_store_dwordx4 v[112:113], v[108:111], off offset:16 nt
	global_load_dwordx4 v[104:107], v[144:145], off offset:64
	s_nop 0
	global_load_dwordx4 v[108:111], v[126:127], off offset:64 nt
	v_pk_mul_f32 v[102:103], v[102:103], v[116:117] op_sel_hi:[1,0]
	v_pk_mul_f32 v[100:101], v[100:101], v[116:117] op_sel_hi:[1,0]
	v_pk_mul_f32 v[98:99], v[98:99], v[116:117] op_sel_hi:[1,0]
	v_pk_mul_f32 v[96:97], v[96:97], v[116:117] op_sel_hi:[1,0]
	v_mul_f32_e32 v100, 0xbfb8aa3b, v100
	v_mul_f32_e32 v101, 0xbfb8aa3b, v101
	v_mul_f32_e32 v102, 0xbfb8aa3b, v102
	v_mul_f32_e32 v103, 0xbfb8aa3b, v103
	v_mul_f32_e32 v96, 0xbfb8aa3b, v96
	v_mul_f32_e32 v97, 0xbfb8aa3b, v97
	v_mul_f32_e32 v98, 0xbfb8aa3b, v98
	v_mul_f32_e32 v99, 0xbfb8aa3b, v99
	v_exp_f32_e32 v100, v100
	v_exp_f32_e32 v101, v101
	v_exp_f32_e32 v102, v102
	v_exp_f32_e32 v103, v103
	v_exp_f32_e32 v96, v96
	v_exp_f32_e32 v97, v97
	v_exp_f32_e32 v98, v98
	v_exp_f32_e32 v99, v99
	v_add_f32_e32 v100, 1.0, v100
	v_add_f32_e32 v101, 1.0, v101
	v_add_f32_e32 v102, 1.0, v102
	v_add_f32_e32 v103, 1.0, v103
	v_add_f32_e32 v116, 1.0, v96
	v_add_f32_e32 v117, 1.0, v97
	v_add_f32_e32 v120, 1.0, v98
	v_add_f32_e32 v121, 1.0, v99
	v_rcp_f32_e32 v96, v100
	v_rcp_f32_e32 v97, v101
	v_rcp_f32_e32 v98, v102
	v_rcp_f32_e32 v99, v103
	v_rcp_f32_e32 v100, v116
	v_rcp_f32_e32 v101, v117
	v_rcp_f32_e32 v102, v120
	v_rcp_f32_e32 v103, v121
	v_or_b32_e32 v114, 32, v142
	v_ashrrev_i32_e32 v115, 31, v114
	v_lshlrev_b64 v[118:119], 6, v[114:115]
	v_lshl_add_u64 v[118:119], s[6:7], 0, v[118:119]
	s_waitcnt vmcnt(1)
	v_lshlrev_b32_e32 v116, 16, v104
	v_and_b32_e32 v117, 0xffff0000, v104
	s_waitcnt vmcnt(0)
	v_lshlrev_b32_e32 v120, 16, v108
	v_and_b32_e32 v121, 0xffff0000, v108
	v_lshlrev_b32_e32 v104, 16, v105
	v_and_b32_e32 v105, 0xffff0000, v105
	v_lshlrev_b32_e32 v108, 16, v109
	v_and_b32_e32 v109, 0xffff0000, v109
	v_lshlrev_b32_e32 v122, 16, v106
	v_and_b32_e32 v123, 0xffff0000, v106
	v_lshlrev_b32_e32 v124, 16, v110
	v_and_b32_e32 v125, 0xffff0000, v110
	v_lshlrev_b32_e32 v106, 16, v107
	v_and_b32_e32 v107, 0xffff0000, v107
	v_lshlrev_b32_e32 v110, 16, v111
	v_and_b32_e32 v111, 0xffff0000, v111
	v_pk_fma_f32 v[96:97], v[96:97], v[120:121], v[116:117]
	v_pk_fma_f32 v[98:99], v[98:99], v[108:109], v[104:105]
	v_pk_fma_f32 v[100:101], v[100:101], v[124:125], v[122:123]
	v_pk_fma_f32 v[102:103], v[102:103], v[110:111], v[106:107]
	global_store_dwordx4 v[112:113], v[96:99], off offset:128 nt
	global_store_dwordx4 v[112:113], v[100:103], off offset:144 nt
	global_load_dwordx4 v[98:101], v[118:119], off
	s_nop 0
	global_load_dwordx4 v[102:105], v[118:119], off offset:16
	global_load_dwordx4 v[106:109], v[118:119], off offset:48
	global_load_dwordx4 v[110:113], v[118:119], off offset:32
	v_lshlrev_b64 v[96:97], 10, v[114:115]
	v_lshl_add_u64 v[96:97], v[96:97], 0, v[140:141]
	v_lshlrev_b64 v[118:119], 1, v[96:97]
	v_lshl_add_u64 v[122:123], s[16:17], 0, v[118:119]
	v_lshl_add_u64 v[124:125], s[14:15], 0, v[118:119]
	global_load_dwordx4 v[114:117], v[122:123], off
	global_load_dwordx4 v[118:121], v[124:125], off nt
	v_lshl_add_u64 v[96:97], v[96:97], 2, s[30:31]
	s_waitcnt vmcnt(5)
	v_mov_b32_e32 v126, v99
	v_mov_b32_e32 v127, v100
	v_mov_b32_e32 v99, v101
	s_waitcnt vmcnt(4)
	v_mov_b32_e32 v100, v103
	v_mov_b32_e32 v101, v104
	v_mov_b32_e32 v103, v105
	v_pk_add_f32 v[98:99], v[126:127], v[98:99]
	v_pk_add_f32 v[100:101], v[100:101], v[102:103]
	v_pk_add_f32 v[98:99], v[98:99], v[98:99] op_sel:[0,1] op_sel_hi:[1,0]
	v_pk_add_f32 v[100:101], v[100:101], v[100:101] op_sel:[0,1] op_sel_hi:[1,0]
	s_waitcnt vmcnt(2)
	v_add_f32_e32 v104, v110, v111
	v_add_f32_e32 v110, v112, v113
	v_mov_b32_e32 v105, v108
	v_mov_b32_e32 v111, v109
	v_mov_b32_e32 v99, v106
	v_mov_b32_e32 v101, v107
	v_pk_add_f32 v[102:103], v[104:105], v[110:111]
	v_pk_add_f32 v[98:99], v[98:99], v[100:101]
	s_waitcnt vmcnt(1)
	v_lshlrev_b32_e32 v108, 16, v114
	v_pk_add_f32 v[98:99], v[98:99], v[102:103]
	v_and_b32_e32 v109, 0xffff0000, v114
	v_add_f32_e32 v98, v98, v99
	v_fmamk_f32 v98, v98, 0x3a800000, v150
	v_mul_f32_e32 v99, 0x4b800000, v98
	v_cmp_gt_f32_e32 vcc, s48, v98
	s_waitcnt vmcnt(0)
	v_lshlrev_b32_e32 v112, 16, v118
	v_and_b32_e32 v113, 0xffff0000, v118
	v_cndmask_b32_e32 v98, v98, v99, vcc
	v_rsq_f32_e32 v100, v98
	v_lshlrev_b32_e32 v114, 16, v115
	v_and_b32_e32 v115, 0xffff0000, v115
	v_lshlrev_b32_e32 v118, 16, v119
	v_mul_f32_e32 v101, 0x45800000, v100
	v_cndmask_b32_e32 v100, v100, v101, vcc
	v_pk_mul_f32 v[94:95], v[94:95], v[100:101] op_sel_hi:[1,0]
	v_pk_mul_f32 v[92:93], v[92:93], v[100:101] op_sel_hi:[1,0]
	v_pk_mul_f32 v[90:91], v[90:91], v[100:101] op_sel_hi:[1,0]
	v_pk_mul_f32 v[88:89], v[88:89], v[100:101] op_sel_hi:[1,0]
	v_mul_f32_e32 v92, 0xbfb8aa3b, v92
	v_mul_f32_e32 v93, 0xbfb8aa3b, v93
	v_mul_f32_e32 v94, 0xbfb8aa3b, v94
	v_mul_f32_e32 v95, 0xbfb8aa3b, v95
	v_mul_f32_e32 v88, 0xbfb8aa3b, v88
	v_mul_f32_e32 v89, 0xbfb8aa3b, v89
	v_mul_f32_e32 v90, 0xbfb8aa3b, v90
	v_mul_f32_e32 v91, 0xbfb8aa3b, v91
	v_exp_f32_e32 v92, v92
	v_exp_f32_e32 v93, v93
	v_exp_f32_e32 v94, v94
	v_exp_f32_e32 v95, v95
	v_exp_f32_e32 v88, v88
	v_exp_f32_e32 v89, v89
	v_exp_f32_e32 v90, v90
	v_exp_f32_e32 v91, v91
	v_add_f32_e32 v92, 1.0, v92
	v_add_f32_e32 v93, 1.0, v93
	v_add_f32_e32 v94, 1.0, v94
	v_add_f32_e32 v95, 1.0, v95
	v_add_f32_e32 v101, 1.0, v88
	v_add_f32_e32 v102, 1.0, v89
	v_add_f32_e32 v103, 1.0, v90
	v_add_f32_e32 v104, 1.0, v91
	v_rcp_f32_e32 v88, v92
	v_rcp_f32_e32 v89, v93
	v_rcp_f32_e32 v90, v94
	v_rcp_f32_e32 v91, v95
	v_rcp_f32_e32 v92, v101
	v_rcp_f32_e32 v93, v102
	v_rcp_f32_e32 v94, v103
	v_rcp_f32_e32 v95, v104
	v_and_b32_e32 v119, 0xffff0000, v119
	v_lshlrev_b32_e32 v144, 16, v116
	v_and_b32_e32 v145, 0xffff0000, v116
	v_lshlrev_b32_e32 v152, 16, v120
	v_and_b32_e32 v153, 0xffff0000, v120
	v_lshlrev_b32_e32 v116, 16, v117
	v_and_b32_e32 v117, 0xffff0000, v117
	v_lshlrev_b32_e32 v98, 16, v121
	v_and_b32_e32 v99, 0xffff0000, v121
	v_pk_fma_f32 v[88:89], v[88:89], v[112:113], v[108:109]
	v_pk_fma_f32 v[90:91], v[90:91], v[118:119], v[114:115]
	v_pk_fma_f32 v[92:93], v[92:93], v[152:153], v[144:145]
	v_pk_fma_f32 v[94:95], v[94:95], v[98:99], v[116:117]
	global_store_dwordx4 v[96:97], v[88:91], off nt
	global_store_dwordx4 v[96:97], v[92:95], off offset:16 nt
	global_load_dwordx4 v[88:91], v[122:123], off offset:64
	s_nop 0
	global_load_dwordx4 v[92:95], v[124:125], off offset:64 nt
	v_pk_mul_f32 v[86:87], v[86:87], v[100:101] op_sel_hi:[1,0]
	v_pk_mul_f32 v[84:85], v[84:85], v[100:101] op_sel_hi:[1,0]
	v_pk_mul_f32 v[82:83], v[82:83], v[100:101] op_sel_hi:[1,0]
	v_pk_mul_f32 v[80:81], v[80:81], v[100:101] op_sel_hi:[1,0]
	v_mul_f32_e32 v84, 0xbfb8aa3b, v84
	v_mul_f32_e32 v85, 0xbfb8aa3b, v85
	v_mul_f32_e32 v86, 0xbfb8aa3b, v86
	v_mul_f32_e32 v87, 0xbfb8aa3b, v87
	v_mul_f32_e32 v80, 0xbfb8aa3b, v80
	v_mul_f32_e32 v81, 0xbfb8aa3b, v81
	v_mul_f32_e32 v82, 0xbfb8aa3b, v82
	v_mul_f32_e32 v83, 0xbfb8aa3b, v83
	v_exp_f32_e32 v84, v84
	v_exp_f32_e32 v85, v85
	v_exp_f32_e32 v86, v86
	v_exp_f32_e32 v87, v87
	v_exp_f32_e32 v80, v80
	v_exp_f32_e32 v81, v81
	v_exp_f32_e32 v82, v82
	v_exp_f32_e32 v83, v83
	v_add_f32_e32 v84, 1.0, v84
	v_add_f32_e32 v85, 1.0, v85
	v_add_f32_e32 v86, 1.0, v86
	v_add_f32_e32 v87, 1.0, v87
	v_add_f32_e32 v100, 1.0, v80
	v_add_f32_e32 v101, 1.0, v81
	v_add_f32_e32 v104, 1.0, v82
	v_add_f32_e32 v105, 1.0, v83
	v_rcp_f32_e32 v80, v84
	v_rcp_f32_e32 v81, v85
	v_rcp_f32_e32 v82, v86
	v_rcp_f32_e32 v83, v87
	v_rcp_f32_e32 v84, v100
	v_rcp_f32_e32 v85, v101
	v_rcp_f32_e32 v86, v104
	v_rcp_f32_e32 v87, v105
	v_or_b32_e32 v98, 48, v142
	v_ashrrev_i32_e32 v99, 31, v98
	v_lshlrev_b64 v[102:103], 6, v[98:99]
	v_lshl_add_u64 v[102:103], s[6:7], 0, v[102:103]
	s_waitcnt vmcnt(1)
	v_lshlrev_b32_e32 v100, 16, v88
	v_and_b32_e32 v101, 0xffff0000, v88
	s_waitcnt vmcnt(0)
	v_lshlrev_b32_e32 v104, 16, v92
	v_and_b32_e32 v105, 0xffff0000, v92
	v_lshlrev_b32_e32 v88, 16, v89
	v_and_b32_e32 v89, 0xffff0000, v89
	v_lshlrev_b32_e32 v92, 16, v93
	v_and_b32_e32 v93, 0xffff0000, v93
	v_lshlrev_b32_e32 v106, 16, v90
	v_and_b32_e32 v107, 0xffff0000, v90
	v_lshlrev_b32_e32 v108, 16, v94
	v_and_b32_e32 v109, 0xffff0000, v94
	v_lshlrev_b32_e32 v90, 16, v91
	v_and_b32_e32 v91, 0xffff0000, v91
	v_lshlrev_b32_e32 v94, 16, v95
	v_and_b32_e32 v95, 0xffff0000, v95
	v_pk_fma_f32 v[80:81], v[80:81], v[104:105], v[100:101]
	v_pk_fma_f32 v[82:83], v[82:83], v[92:93], v[88:89]
	v_pk_fma_f32 v[84:85], v[84:85], v[108:109], v[106:107]
	v_pk_fma_f32 v[86:87], v[86:87], v[94:95], v[90:91]
	global_store_dwordx4 v[96:97], v[80:83], off offset:128 nt
	global_store_dwordx4 v[96:97], v[84:87], off offset:144 nt
	global_load_dwordx4 v[82:85], v[102:103], off
	s_nop 0
	global_load_dwordx4 v[86:89], v[102:103], off offset:16
	global_load_dwordx4 v[90:93], v[102:103], off offset:48
	global_load_dwordx4 v[94:97], v[102:103], off offset:32
	v_lshlrev_b64 v[80:81], 10, v[98:99]
	v_lshl_add_u64 v[80:81], v[80:81], 0, v[140:141]
	v_lshlrev_b64 v[102:103], 1, v[80:81]
	v_lshl_add_u64 v[106:107], s[16:17], 0, v[102:103]
	v_lshl_add_u64 v[108:109], s[14:15], 0, v[102:103]
	global_load_dwordx4 v[98:101], v[106:107], off
	global_load_dwordx4 v[102:105], v[108:109], off nt
	v_lshl_add_u64 v[80:81], v[80:81], 2, s[30:31]
	s_waitcnt vmcnt(5)
	v_mov_b32_e32 v110, v83
	v_mov_b32_e32 v111, v84
	v_mov_b32_e32 v83, v85
	s_waitcnt vmcnt(4)
	v_mov_b32_e32 v84, v87
	v_mov_b32_e32 v85, v88
	v_mov_b32_e32 v87, v89
	v_pk_add_f32 v[82:83], v[110:111], v[82:83]
	v_pk_add_f32 v[84:85], v[84:85], v[86:87]
	v_pk_add_f32 v[82:83], v[82:83], v[82:83] op_sel:[0,1] op_sel_hi:[1,0]
	v_pk_add_f32 v[84:85], v[84:85], v[84:85] op_sel:[0,1] op_sel_hi:[1,0]
	s_waitcnt vmcnt(2)
	v_add_f32_e32 v88, v94, v95
	v_add_f32_e32 v94, v96, v97
	v_mov_b32_e32 v89, v92
	v_mov_b32_e32 v95, v93
	v_mov_b32_e32 v83, v90
	v_mov_b32_e32 v85, v91
	v_pk_add_f32 v[86:87], v[88:89], v[94:95]
	v_pk_add_f32 v[82:83], v[82:83], v[84:85]
	s_waitcnt vmcnt(1)
	v_lshlrev_b32_e32 v92, 16, v98
	v_pk_add_f32 v[82:83], v[82:83], v[86:87]
	v_and_b32_e32 v93, 0xffff0000, v98
	v_add_f32_e32 v82, v82, v83
	v_fmamk_f32 v82, v82, 0x3a800000, v150
	v_mul_f32_e32 v83, 0x4b800000, v82
	v_cmp_gt_f32_e32 vcc, s48, v82
	s_waitcnt vmcnt(0)
	v_lshlrev_b32_e32 v96, 16, v102
	v_and_b32_e32 v97, 0xffff0000, v102
	v_cndmask_b32_e32 v82, v82, v83, vcc
	v_rsq_f32_e32 v84, v82
	v_lshlrev_b32_e32 v98, 16, v99
	v_and_b32_e32 v99, 0xffff0000, v99
	v_lshlrev_b32_e32 v102, 16, v103
	v_mul_f32_e32 v85, 0x45800000, v84
	v_cndmask_b32_e32 v84, v84, v85, vcc
	v_pk_mul_f32 v[78:79], v[78:79], v[84:85] op_sel_hi:[1,0]
	v_pk_mul_f32 v[76:77], v[76:77], v[84:85] op_sel_hi:[1,0]
	v_pk_mul_f32 v[74:75], v[74:75], v[84:85] op_sel_hi:[1,0]
	v_pk_mul_f32 v[72:73], v[72:73], v[84:85] op_sel_hi:[1,0]
	v_mul_f32_e32 v76, 0xbfb8aa3b, v76
	v_mul_f32_e32 v77, 0xbfb8aa3b, v77
	v_mul_f32_e32 v78, 0xbfb8aa3b, v78
	v_mul_f32_e32 v79, 0xbfb8aa3b, v79
	v_mul_f32_e32 v72, 0xbfb8aa3b, v72
	v_mul_f32_e32 v73, 0xbfb8aa3b, v73
	v_mul_f32_e32 v74, 0xbfb8aa3b, v74
	v_mul_f32_e32 v75, 0xbfb8aa3b, v75
	v_exp_f32_e32 v76, v76
	v_exp_f32_e32 v77, v77
	v_exp_f32_e32 v78, v78
	v_exp_f32_e32 v79, v79
	v_exp_f32_e32 v72, v72
	v_exp_f32_e32 v73, v73
	v_exp_f32_e32 v74, v74
	v_exp_f32_e32 v75, v75
	v_add_f32_e32 v76, 1.0, v76
	v_add_f32_e32 v77, 1.0, v77
	v_add_f32_e32 v78, 1.0, v78
	v_add_f32_e32 v79, 1.0, v79
	v_add_f32_e32 v85, 1.0, v72
	v_add_f32_e32 v86, 1.0, v73
	v_add_f32_e32 v87, 1.0, v74
	v_add_f32_e32 v88, 1.0, v75
	v_rcp_f32_e32 v72, v76
	v_rcp_f32_e32 v73, v77
	v_rcp_f32_e32 v74, v78
	v_rcp_f32_e32 v75, v79
	v_rcp_f32_e32 v76, v85
	v_rcp_f32_e32 v77, v86
	v_rcp_f32_e32 v78, v87
	v_rcp_f32_e32 v79, v88
	v_and_b32_e32 v103, 0xffff0000, v103
	v_lshlrev_b32_e32 v112, 16, v100
	v_and_b32_e32 v113, 0xffff0000, v100
	v_lshlrev_b32_e32 v114, 16, v104
	v_and_b32_e32 v115, 0xffff0000, v104
	v_lshlrev_b32_e32 v100, 16, v101
	v_and_b32_e32 v101, 0xffff0000, v101
	v_lshlrev_b32_e32 v82, 16, v105
	v_and_b32_e32 v83, 0xffff0000, v105
	v_pk_fma_f32 v[72:73], v[72:73], v[96:97], v[92:93]
	v_pk_fma_f32 v[74:75], v[74:75], v[102:103], v[98:99]
	v_pk_fma_f32 v[76:77], v[76:77], v[114:115], v[112:113]
	v_pk_fma_f32 v[78:79], v[78:79], v[82:83], v[100:101]
	global_store_dwordx4 v[80:81], v[72:75], off nt
	global_store_dwordx4 v[80:81], v[76:79], off offset:16 nt
	global_load_dwordx4 v[72:75], v[106:107], off offset:64
	s_nop 0
	global_load_dwordx4 v[76:79], v[108:109], off offset:64 nt
	v_pk_mul_f32 v[70:71], v[70:71], v[84:85] op_sel_hi:[1,0]
	v_pk_mul_f32 v[68:69], v[68:69], v[84:85] op_sel_hi:[1,0]
	v_pk_mul_f32 v[66:67], v[66:67], v[84:85] op_sel_hi:[1,0]
	v_pk_mul_f32 v[64:65], v[64:65], v[84:85] op_sel_hi:[1,0]
	v_mul_f32_e32 v68, 0xbfb8aa3b, v68
	v_mul_f32_e32 v69, 0xbfb8aa3b, v69
	v_mul_f32_e32 v70, 0xbfb8aa3b, v70
	v_mul_f32_e32 v71, 0xbfb8aa3b, v71
	v_mul_f32_e32 v64, 0xbfb8aa3b, v64
	v_mul_f32_e32 v65, 0xbfb8aa3b, v65
	v_mul_f32_e32 v66, 0xbfb8aa3b, v66
	v_mul_f32_e32 v67, 0xbfb8aa3b, v67
	v_exp_f32_e32 v68, v68
	v_exp_f32_e32 v69, v69
	v_exp_f32_e32 v70, v70
	v_exp_f32_e32 v71, v71
	v_exp_f32_e32 v64, v64
	v_exp_f32_e32 v65, v65
	v_exp_f32_e32 v66, v66
	v_exp_f32_e32 v67, v67
	v_add_f32_e32 v68, 1.0, v68
	v_add_f32_e32 v69, 1.0, v69
	v_add_f32_e32 v70, 1.0, v70
	v_add_f32_e32 v71, 1.0, v71
	v_add_f32_e32 v84, 1.0, v64
	v_add_f32_e32 v85, 1.0, v65
	v_add_f32_e32 v88, 1.0, v66
	v_add_f32_e32 v89, 1.0, v67
	v_rcp_f32_e32 v64, v68
	v_rcp_f32_e32 v65, v69
	v_rcp_f32_e32 v66, v70
	v_rcp_f32_e32 v67, v71
	v_rcp_f32_e32 v68, v84
	v_rcp_f32_e32 v69, v85
	v_rcp_f32_e32 v70, v88
	v_rcp_f32_e32 v71, v89
	v_add_u32_e32 v82, 0x80, v142
	v_ashrrev_i32_e32 v83, 31, v82
	v_lshlrev_b64 v[86:87], 6, v[82:83]
	v_lshl_add_u64 v[86:87], s[6:7], 0, v[86:87]
	s_waitcnt vmcnt(1)
	v_lshlrev_b32_e32 v84, 16, v72
	v_and_b32_e32 v85, 0xffff0000, v72
	s_waitcnt vmcnt(0)
	v_lshlrev_b32_e32 v88, 16, v76
	v_and_b32_e32 v89, 0xffff0000, v76
	v_lshlrev_b32_e32 v72, 16, v73
	v_and_b32_e32 v73, 0xffff0000, v73
	v_lshlrev_b32_e32 v76, 16, v77
	v_and_b32_e32 v77, 0xffff0000, v77
	v_lshlrev_b32_e32 v90, 16, v74
	v_and_b32_e32 v91, 0xffff0000, v74
	v_lshlrev_b32_e32 v92, 16, v78
	v_and_b32_e32 v93, 0xffff0000, v78
	v_lshlrev_b32_e32 v74, 16, v75
	v_and_b32_e32 v75, 0xffff0000, v75
	v_lshlrev_b32_e32 v78, 16, v79
	v_and_b32_e32 v79, 0xffff0000, v79
	v_pk_fma_f32 v[64:65], v[64:65], v[88:89], v[84:85]
	v_pk_fma_f32 v[66:67], v[66:67], v[76:77], v[72:73]
	v_pk_fma_f32 v[68:69], v[68:69], v[92:93], v[90:91]
	v_pk_fma_f32 v[70:71], v[70:71], v[78:79], v[74:75]
	global_store_dwordx4 v[80:81], v[64:67], off offset:128 nt
	global_store_dwordx4 v[80:81], v[68:71], off offset:144 nt
	global_load_dwordx4 v[66:69], v[86:87], off
	s_nop 0
	global_load_dwordx4 v[70:73], v[86:87], off offset:16
	global_load_dwordx4 v[74:77], v[86:87], off offset:48
	global_load_dwordx4 v[78:81], v[86:87], off offset:32
	v_lshlrev_b64 v[64:65], 10, v[82:83]
	v_lshl_add_u64 v[64:65], v[64:65], 0, v[140:141]
	v_lshlrev_b64 v[86:87], 1, v[64:65]
	v_lshl_add_u64 v[90:91], s[16:17], 0, v[86:87]
	v_lshl_add_u64 v[92:93], s[14:15], 0, v[86:87]
	global_load_dwordx4 v[82:85], v[90:91], off
	global_load_dwordx4 v[86:89], v[92:93], off nt
	v_lshl_add_u64 v[64:65], v[64:65], 2, s[30:31]
	s_waitcnt vmcnt(5)
	v_mov_b32_e32 v94, v67
	v_mov_b32_e32 v95, v68
	v_mov_b32_e32 v67, v69
	s_waitcnt vmcnt(4)
	v_mov_b32_e32 v68, v71
	v_mov_b32_e32 v69, v72
	v_mov_b32_e32 v71, v73
	v_pk_add_f32 v[66:67], v[94:95], v[66:67]
	v_pk_add_f32 v[68:69], v[68:69], v[70:71]
	v_pk_add_f32 v[66:67], v[66:67], v[66:67] op_sel:[0,1] op_sel_hi:[1,0]
	v_pk_add_f32 v[68:69], v[68:69], v[68:69] op_sel:[0,1] op_sel_hi:[1,0]
	s_waitcnt vmcnt(2)
	v_add_f32_e32 v72, v78, v79
	v_add_f32_e32 v78, v80, v81
	v_mov_b32_e32 v73, v76
	v_mov_b32_e32 v79, v77
	v_mov_b32_e32 v67, v74
	v_mov_b32_e32 v69, v75
	v_pk_add_f32 v[70:71], v[72:73], v[78:79]
	v_pk_add_f32 v[66:67], v[66:67], v[68:69]
	s_waitcnt vmcnt(1)
	v_lshlrev_b32_e32 v76, 16, v82
	v_pk_add_f32 v[66:67], v[66:67], v[70:71]
	v_and_b32_e32 v77, 0xffff0000, v82
	v_add_f32_e32 v66, v66, v67
	v_fmamk_f32 v66, v66, 0x3a800000, v150
	v_mul_f32_e32 v67, 0x4b800000, v66
	v_cmp_gt_f32_e32 vcc, s48, v66
	s_waitcnt vmcnt(0)
	v_lshlrev_b32_e32 v80, 16, v86
	v_and_b32_e32 v81, 0xffff0000, v86
	v_cndmask_b32_e32 v66, v66, v67, vcc
	v_rsq_f32_e32 v68, v66
	v_lshlrev_b32_e32 v82, 16, v83
	v_and_b32_e32 v83, 0xffff0000, v83
	v_lshlrev_b32_e32 v86, 16, v87
	v_mul_f32_e32 v69, 0x45800000, v68
	v_cndmask_b32_e32 v68, v68, v69, vcc
	v_pk_mul_f32 v[62:63], v[62:63], v[68:69] op_sel_hi:[1,0]
	v_pk_mul_f32 v[60:61], v[60:61], v[68:69] op_sel_hi:[1,0]
	v_pk_mul_f32 v[58:59], v[58:59], v[68:69] op_sel_hi:[1,0]
	v_pk_mul_f32 v[56:57], v[56:57], v[68:69] op_sel_hi:[1,0]
	v_mul_f32_e32 v60, 0xbfb8aa3b, v60
	v_mul_f32_e32 v61, 0xbfb8aa3b, v61
	v_mul_f32_e32 v62, 0xbfb8aa3b, v62
	v_mul_f32_e32 v63, 0xbfb8aa3b, v63
	v_mul_f32_e32 v56, 0xbfb8aa3b, v56
	v_mul_f32_e32 v57, 0xbfb8aa3b, v57
	v_mul_f32_e32 v58, 0xbfb8aa3b, v58
	v_mul_f32_e32 v59, 0xbfb8aa3b, v59
	v_exp_f32_e32 v60, v60
	v_exp_f32_e32 v61, v61
	v_exp_f32_e32 v62, v62
	v_exp_f32_e32 v63, v63
	v_exp_f32_e32 v56, v56
	v_exp_f32_e32 v57, v57
	v_exp_f32_e32 v58, v58
	v_exp_f32_e32 v59, v59
	v_add_f32_e32 v60, 1.0, v60
	v_add_f32_e32 v61, 1.0, v61
	v_add_f32_e32 v62, 1.0, v62
	v_add_f32_e32 v63, 1.0, v63
	v_add_f32_e32 v69, 1.0, v56
	v_add_f32_e32 v70, 1.0, v57
	v_add_f32_e32 v71, 1.0, v58
	v_add_f32_e32 v72, 1.0, v59
	v_rcp_f32_e32 v56, v60
	v_rcp_f32_e32 v57, v61
	v_rcp_f32_e32 v58, v62
	v_rcp_f32_e32 v59, v63
	v_rcp_f32_e32 v60, v69
	v_rcp_f32_e32 v61, v70
	v_rcp_f32_e32 v62, v71
	v_rcp_f32_e32 v63, v72
	v_and_b32_e32 v87, 0xffff0000, v87
	v_lshlrev_b32_e32 v96, 16, v84
	v_and_b32_e32 v97, 0xffff0000, v84
	v_lshlrev_b32_e32 v98, 16, v88
	v_and_b32_e32 v99, 0xffff0000, v88
	v_lshlrev_b32_e32 v84, 16, v85
	v_and_b32_e32 v85, 0xffff0000, v85
	v_lshlrev_b32_e32 v66, 16, v89
	v_and_b32_e32 v67, 0xffff0000, v89
	v_pk_fma_f32 v[56:57], v[56:57], v[80:81], v[76:77]
	v_pk_fma_f32 v[58:59], v[58:59], v[86:87], v[82:83]
	v_pk_fma_f32 v[60:61], v[60:61], v[98:99], v[96:97]
	v_pk_fma_f32 v[62:63], v[62:63], v[66:67], v[84:85]
	global_store_dwordx4 v[64:65], v[56:59], off nt
	global_store_dwordx4 v[64:65], v[60:63], off offset:16 nt
	global_load_dwordx4 v[56:59], v[90:91], off offset:64
	s_nop 0
	global_load_dwordx4 v[60:63], v[92:93], off offset:64 nt
	v_pk_mul_f32 v[54:55], v[54:55], v[68:69] op_sel_hi:[1,0]
	v_pk_mul_f32 v[52:53], v[52:53], v[68:69] op_sel_hi:[1,0]
	v_pk_mul_f32 v[50:51], v[50:51], v[68:69] op_sel_hi:[1,0]
	v_pk_mul_f32 v[48:49], v[48:49], v[68:69] op_sel_hi:[1,0]
	v_mul_f32_e32 v52, 0xbfb8aa3b, v52
	v_mul_f32_e32 v53, 0xbfb8aa3b, v53
	v_mul_f32_e32 v54, 0xbfb8aa3b, v54
	v_mul_f32_e32 v55, 0xbfb8aa3b, v55
	v_mul_f32_e32 v48, 0xbfb8aa3b, v48
	v_mul_f32_e32 v49, 0xbfb8aa3b, v49
	v_mul_f32_e32 v50, 0xbfb8aa3b, v50
	v_mul_f32_e32 v51, 0xbfb8aa3b, v51
	v_exp_f32_e32 v52, v52
	v_exp_f32_e32 v53, v53
	v_exp_f32_e32 v54, v54
	v_exp_f32_e32 v55, v55
	v_exp_f32_e32 v48, v48
	v_exp_f32_e32 v49, v49
	v_exp_f32_e32 v50, v50
	v_exp_f32_e32 v51, v51
	v_add_f32_e32 v52, 1.0, v52
	v_add_f32_e32 v53, 1.0, v53
	v_add_f32_e32 v54, 1.0, v54
	v_add_f32_e32 v55, 1.0, v55
	v_add_f32_e32 v68, 1.0, v48
	v_add_f32_e32 v69, 1.0, v49
	v_add_f32_e32 v72, 1.0, v50
	v_add_f32_e32 v73, 1.0, v51
	v_rcp_f32_e32 v48, v52
	v_rcp_f32_e32 v49, v53
	v_rcp_f32_e32 v50, v54
	v_rcp_f32_e32 v51, v55
	v_rcp_f32_e32 v52, v68
	v_rcp_f32_e32 v53, v69
	v_rcp_f32_e32 v54, v72
	v_rcp_f32_e32 v55, v73
	v_add_u32_e32 v66, 0x90, v142
	v_ashrrev_i32_e32 v67, 31, v66
	v_lshlrev_b64 v[70:71], 6, v[66:67]
	v_lshl_add_u64 v[70:71], s[6:7], 0, v[70:71]
	s_waitcnt vmcnt(1)
	v_lshlrev_b32_e32 v68, 16, v56
	v_and_b32_e32 v69, 0xffff0000, v56
	s_waitcnt vmcnt(0)
	v_lshlrev_b32_e32 v72, 16, v60
	v_and_b32_e32 v73, 0xffff0000, v60
	v_lshlrev_b32_e32 v56, 16, v57
	v_and_b32_e32 v57, 0xffff0000, v57
	v_lshlrev_b32_e32 v60, 16, v61
	v_and_b32_e32 v61, 0xffff0000, v61
	v_lshlrev_b32_e32 v74, 16, v58
	v_and_b32_e32 v75, 0xffff0000, v58
	v_lshlrev_b32_e32 v76, 16, v62
	v_and_b32_e32 v77, 0xffff0000, v62
	v_lshlrev_b32_e32 v58, 16, v59
	v_and_b32_e32 v59, 0xffff0000, v59
	v_lshlrev_b32_e32 v62, 16, v63
	v_and_b32_e32 v63, 0xffff0000, v63
	v_pk_fma_f32 v[48:49], v[48:49], v[72:73], v[68:69]
	v_pk_fma_f32 v[50:51], v[50:51], v[60:61], v[56:57]
	v_pk_fma_f32 v[52:53], v[52:53], v[76:77], v[74:75]
	v_pk_fma_f32 v[54:55], v[54:55], v[62:63], v[58:59]
	global_store_dwordx4 v[64:65], v[48:51], off offset:128 nt
	global_store_dwordx4 v[64:65], v[52:55], off offset:144 nt
	global_load_dwordx4 v[50:53], v[70:71], off
	s_nop 0
	global_load_dwordx4 v[54:57], v[70:71], off offset:16
	global_load_dwordx4 v[58:61], v[70:71], off offset:48
	global_load_dwordx4 v[62:65], v[70:71], off offset:32
	v_lshlrev_b64 v[48:49], 10, v[66:67]
	v_lshl_add_u64 v[48:49], v[48:49], 0, v[140:141]
	v_lshlrev_b64 v[70:71], 1, v[48:49]
	v_lshl_add_u64 v[74:75], s[16:17], 0, v[70:71]
	v_lshl_add_u64 v[76:77], s[14:15], 0, v[70:71]
	global_load_dwordx4 v[66:69], v[74:75], off
	global_load_dwordx4 v[70:73], v[76:77], off nt
	v_lshl_add_u64 v[48:49], v[48:49], 2, s[30:31]
	s_waitcnt vmcnt(5)
	v_mov_b32_e32 v78, v51
	v_mov_b32_e32 v79, v52
	v_mov_b32_e32 v51, v53
	s_waitcnt vmcnt(4)
	v_mov_b32_e32 v52, v55
	v_mov_b32_e32 v53, v56
	v_mov_b32_e32 v55, v57
	v_pk_add_f32 v[50:51], v[78:79], v[50:51]
	v_pk_add_f32 v[52:53], v[52:53], v[54:55]
	v_pk_add_f32 v[50:51], v[50:51], v[50:51] op_sel:[0,1] op_sel_hi:[1,0]
	v_pk_add_f32 v[52:53], v[52:53], v[52:53] op_sel:[0,1] op_sel_hi:[1,0]
	s_waitcnt vmcnt(2)
	v_add_f32_e32 v56, v62, v63
	v_add_f32_e32 v62, v64, v65
	v_mov_b32_e32 v57, v60
	v_mov_b32_e32 v63, v61
	v_mov_b32_e32 v51, v58
	v_mov_b32_e32 v53, v59
	v_pk_add_f32 v[54:55], v[56:57], v[62:63]
	v_pk_add_f32 v[50:51], v[50:51], v[52:53]
	s_waitcnt vmcnt(1)
	v_lshlrev_b32_e32 v60, 16, v66
	v_pk_add_f32 v[50:51], v[50:51], v[54:55]
	v_and_b32_e32 v61, 0xffff0000, v66
	v_add_f32_e32 v50, v50, v51
	v_fmamk_f32 v50, v50, 0x3a800000, v150
	v_mul_f32_e32 v51, 0x4b800000, v50
	v_cmp_gt_f32_e32 vcc, s48, v50
	s_waitcnt vmcnt(0)
	v_lshlrev_b32_e32 v64, 16, v70
	v_and_b32_e32 v65, 0xffff0000, v70
	v_cndmask_b32_e32 v50, v50, v51, vcc
	v_rsq_f32_e32 v52, v50
	v_lshlrev_b32_e32 v66, 16, v67
	v_and_b32_e32 v67, 0xffff0000, v67
	v_lshlrev_b32_e32 v70, 16, v71
	v_mul_f32_e32 v53, 0x45800000, v52
	v_cndmask_b32_e32 v52, v52, v53, vcc
	v_pk_mul_f32 v[46:47], v[46:47], v[52:53] op_sel_hi:[1,0]
	v_pk_mul_f32 v[44:45], v[44:45], v[52:53] op_sel_hi:[1,0]
	v_pk_mul_f32 v[42:43], v[42:43], v[52:53] op_sel_hi:[1,0]
	v_pk_mul_f32 v[40:41], v[40:41], v[52:53] op_sel_hi:[1,0]
	v_mul_f32_e32 v44, 0xbfb8aa3b, v44
	v_mul_f32_e32 v45, 0xbfb8aa3b, v45
	v_mul_f32_e32 v46, 0xbfb8aa3b, v46
	v_mul_f32_e32 v47, 0xbfb8aa3b, v47
	v_mul_f32_e32 v40, 0xbfb8aa3b, v40
	v_mul_f32_e32 v41, 0xbfb8aa3b, v41
	v_mul_f32_e32 v42, 0xbfb8aa3b, v42
	v_mul_f32_e32 v43, 0xbfb8aa3b, v43
	v_exp_f32_e32 v44, v44
	v_exp_f32_e32 v45, v45
	v_exp_f32_e32 v46, v46
	v_exp_f32_e32 v47, v47
	v_exp_f32_e32 v40, v40
	v_exp_f32_e32 v41, v41
	v_exp_f32_e32 v42, v42
	v_exp_f32_e32 v43, v43
	v_add_f32_e32 v44, 1.0, v44
	v_add_f32_e32 v45, 1.0, v45
	v_add_f32_e32 v46, 1.0, v46
	v_add_f32_e32 v47, 1.0, v47
	v_add_f32_e32 v53, 1.0, v40
	v_add_f32_e32 v54, 1.0, v41
	v_add_f32_e32 v55, 1.0, v42
	v_add_f32_e32 v56, 1.0, v43
	v_rcp_f32_e32 v40, v44
	v_rcp_f32_e32 v41, v45
	v_rcp_f32_e32 v42, v46
	v_rcp_f32_e32 v43, v47
	v_rcp_f32_e32 v44, v53
	v_rcp_f32_e32 v45, v54
	v_rcp_f32_e32 v46, v55
	v_rcp_f32_e32 v47, v56
	v_and_b32_e32 v71, 0xffff0000, v71
	v_lshlrev_b32_e32 v80, 16, v68
	v_and_b32_e32 v81, 0xffff0000, v68
	v_lshlrev_b32_e32 v82, 16, v72
	v_and_b32_e32 v83, 0xffff0000, v72
	v_lshlrev_b32_e32 v68, 16, v69
	v_and_b32_e32 v69, 0xffff0000, v69
	v_lshlrev_b32_e32 v50, 16, v73
	v_and_b32_e32 v51, 0xffff0000, v73
	v_pk_fma_f32 v[40:41], v[40:41], v[64:65], v[60:61]
	v_pk_fma_f32 v[42:43], v[42:43], v[70:71], v[66:67]
	v_pk_fma_f32 v[44:45], v[44:45], v[82:83], v[80:81]
	v_pk_fma_f32 v[46:47], v[46:47], v[50:51], v[68:69]
	global_store_dwordx4 v[48:49], v[40:43], off nt
	global_store_dwordx4 v[48:49], v[44:47], off offset:16 nt
	global_load_dwordx4 v[40:43], v[74:75], off offset:64
	s_nop 0
	global_load_dwordx4 v[44:47], v[76:77], off offset:64 nt
	v_pk_mul_f32 v[38:39], v[38:39], v[52:53] op_sel_hi:[1,0]
	v_pk_mul_f32 v[36:37], v[36:37], v[52:53] op_sel_hi:[1,0]
	v_pk_mul_f32 v[34:35], v[34:35], v[52:53] op_sel_hi:[1,0]
	v_pk_mul_f32 v[32:33], v[32:33], v[52:53] op_sel_hi:[1,0]
	v_mul_f32_e32 v36, 0xbfb8aa3b, v36
	v_mul_f32_e32 v37, 0xbfb8aa3b, v37
	v_mul_f32_e32 v38, 0xbfb8aa3b, v38
	v_mul_f32_e32 v39, 0xbfb8aa3b, v39
	v_mul_f32_e32 v32, 0xbfb8aa3b, v32
	v_mul_f32_e32 v33, 0xbfb8aa3b, v33
	v_mul_f32_e32 v34, 0xbfb8aa3b, v34
	v_mul_f32_e32 v35, 0xbfb8aa3b, v35
	v_exp_f32_e32 v36, v36
	v_exp_f32_e32 v37, v37
	v_exp_f32_e32 v38, v38
	v_exp_f32_e32 v39, v39
	v_exp_f32_e32 v32, v32
	v_exp_f32_e32 v33, v33
	v_exp_f32_e32 v34, v34
	v_exp_f32_e32 v35, v35
	v_add_f32_e32 v36, 1.0, v36
	v_add_f32_e32 v37, 1.0, v37
	v_add_f32_e32 v38, 1.0, v38
	v_add_f32_e32 v39, 1.0, v39
	v_add_f32_e32 v52, 1.0, v32
	v_add_f32_e32 v53, 1.0, v33
	v_add_f32_e32 v56, 1.0, v34
	v_add_f32_e32 v57, 1.0, v35
	v_rcp_f32_e32 v32, v36
	v_rcp_f32_e32 v33, v37
	v_rcp_f32_e32 v34, v38
	v_rcp_f32_e32 v35, v39
	v_rcp_f32_e32 v36, v52
	v_rcp_f32_e32 v37, v53
	v_rcp_f32_e32 v38, v56
	v_rcp_f32_e32 v39, v57
	v_add_u32_e32 v50, 0xa0, v142
	v_ashrrev_i32_e32 v51, 31, v50
	v_lshlrev_b64 v[54:55], 6, v[50:51]
	v_lshl_add_u64 v[54:55], s[6:7], 0, v[54:55]
	s_waitcnt vmcnt(1)
	v_lshlrev_b32_e32 v52, 16, v40
	v_and_b32_e32 v53, 0xffff0000, v40
	s_waitcnt vmcnt(0)
	v_lshlrev_b32_e32 v56, 16, v44
	v_and_b32_e32 v57, 0xffff0000, v44
	v_lshlrev_b32_e32 v40, 16, v41
	v_and_b32_e32 v41, 0xffff0000, v41
	v_lshlrev_b32_e32 v44, 16, v45
	v_and_b32_e32 v45, 0xffff0000, v45
	v_lshlrev_b32_e32 v58, 16, v42
	v_and_b32_e32 v59, 0xffff0000, v42
	v_lshlrev_b32_e32 v60, 16, v46
	v_and_b32_e32 v61, 0xffff0000, v46
	v_lshlrev_b32_e32 v42, 16, v43
	v_and_b32_e32 v43, 0xffff0000, v43
	v_lshlrev_b32_e32 v46, 16, v47
	v_and_b32_e32 v47, 0xffff0000, v47
	v_pk_fma_f32 v[32:33], v[32:33], v[56:57], v[52:53]
	v_pk_fma_f32 v[34:35], v[34:35], v[44:45], v[40:41]
	v_pk_fma_f32 v[36:37], v[36:37], v[60:61], v[58:59]
	v_pk_fma_f32 v[38:39], v[38:39], v[46:47], v[42:43]
	global_store_dwordx4 v[48:49], v[32:35], off offset:128 nt
	global_store_dwordx4 v[48:49], v[36:39], off offset:144 nt
	global_load_dwordx4 v[34:37], v[54:55], off
	s_nop 0
	global_load_dwordx4 v[38:41], v[54:55], off offset:16
	global_load_dwordx4 v[42:45], v[54:55], off offset:48
	global_load_dwordx4 v[46:49], v[54:55], off offset:32
	v_lshlrev_b64 v[32:33], 10, v[50:51]
	v_lshl_add_u64 v[32:33], v[32:33], 0, v[140:141]
	v_lshlrev_b64 v[54:55], 1, v[32:33]
	v_lshl_add_u64 v[58:59], s[16:17], 0, v[54:55]
	v_lshl_add_u64 v[60:61], s[14:15], 0, v[54:55]
	global_load_dwordx4 v[50:53], v[58:59], off
	global_load_dwordx4 v[54:57], v[60:61], off nt
	v_lshl_add_u64 v[32:33], v[32:33], 2, s[30:31]
	s_waitcnt vmcnt(5)
	v_mov_b32_e32 v62, v35
	v_mov_b32_e32 v63, v36
	v_mov_b32_e32 v35, v37
	s_waitcnt vmcnt(4)
	v_mov_b32_e32 v36, v39
	v_mov_b32_e32 v37, v40
	v_mov_b32_e32 v39, v41
	v_pk_add_f32 v[34:35], v[62:63], v[34:35]
	v_pk_add_f32 v[36:37], v[36:37], v[38:39]
	v_pk_add_f32 v[34:35], v[34:35], v[34:35] op_sel:[0,1] op_sel_hi:[1,0]
	v_pk_add_f32 v[36:37], v[36:37], v[36:37] op_sel:[0,1] op_sel_hi:[1,0]
	s_waitcnt vmcnt(2)
	v_add_f32_e32 v40, v46, v47
	v_add_f32_e32 v46, v48, v49
	v_mov_b32_e32 v41, v44
	v_mov_b32_e32 v47, v45
	v_mov_b32_e32 v35, v42
	v_mov_b32_e32 v37, v43
	v_pk_add_f32 v[38:39], v[40:41], v[46:47]
	v_pk_add_f32 v[34:35], v[34:35], v[36:37]
	s_waitcnt vmcnt(1)
	v_lshlrev_b32_e32 v44, 16, v50
	v_pk_add_f32 v[34:35], v[34:35], v[38:39]
	v_and_b32_e32 v45, 0xffff0000, v50
	v_add_f32_e32 v34, v34, v35
	v_fmamk_f32 v34, v34, 0x3a800000, v150
	v_mul_f32_e32 v35, 0x4b800000, v34
	v_cmp_gt_f32_e32 vcc, s48, v34
	s_waitcnt vmcnt(0)
	v_lshlrev_b32_e32 v48, 16, v54
	v_and_b32_e32 v49, 0xffff0000, v54
	v_cndmask_b32_e32 v34, v34, v35, vcc
	v_rsq_f32_e32 v36, v34
	v_lshlrev_b32_e32 v50, 16, v51
	v_and_b32_e32 v51, 0xffff0000, v51
	v_lshlrev_b32_e32 v54, 16, v55
	v_mul_f32_e32 v37, 0x45800000, v36
	v_cndmask_b32_e32 v36, v36, v37, vcc
	v_pk_mul_f32 v[30:31], v[30:31], v[36:37] op_sel_hi:[1,0]
	v_pk_mul_f32 v[28:29], v[28:29], v[36:37] op_sel_hi:[1,0]
	v_pk_mul_f32 v[26:27], v[26:27], v[36:37] op_sel_hi:[1,0]
	v_pk_mul_f32 v[24:25], v[24:25], v[36:37] op_sel_hi:[1,0]
	v_mul_f32_e32 v28, 0xbfb8aa3b, v28
	v_mul_f32_e32 v29, 0xbfb8aa3b, v29
	v_mul_f32_e32 v30, 0xbfb8aa3b, v30
	v_mul_f32_e32 v31, 0xbfb8aa3b, v31
	v_mul_f32_e32 v24, 0xbfb8aa3b, v24
	v_mul_f32_e32 v25, 0xbfb8aa3b, v25
	v_mul_f32_e32 v26, 0xbfb8aa3b, v26
	v_mul_f32_e32 v27, 0xbfb8aa3b, v27
	v_exp_f32_e32 v28, v28
	v_exp_f32_e32 v29, v29
	v_exp_f32_e32 v30, v30
	v_exp_f32_e32 v31, v31
	v_exp_f32_e32 v24, v24
	v_exp_f32_e32 v25, v25
	v_exp_f32_e32 v26, v26
	v_exp_f32_e32 v27, v27
	v_add_f32_e32 v28, 1.0, v28
	v_add_f32_e32 v29, 1.0, v29
	v_add_f32_e32 v30, 1.0, v30
	v_add_f32_e32 v31, 1.0, v31
	v_add_f32_e32 v37, 1.0, v24
	v_add_f32_e32 v38, 1.0, v25
	v_add_f32_e32 v39, 1.0, v26
	v_add_f32_e32 v40, 1.0, v27
	v_rcp_f32_e32 v24, v28
	v_rcp_f32_e32 v25, v29
	v_rcp_f32_e32 v26, v30
	v_rcp_f32_e32 v27, v31
	v_rcp_f32_e32 v28, v37
	v_rcp_f32_e32 v29, v38
	v_rcp_f32_e32 v30, v39
	v_rcp_f32_e32 v31, v40
	v_and_b32_e32 v55, 0xffff0000, v55
	v_lshlrev_b32_e32 v64, 16, v52
	v_and_b32_e32 v65, 0xffff0000, v52
	v_lshlrev_b32_e32 v66, 16, v56
	v_and_b32_e32 v67, 0xffff0000, v56
	v_lshlrev_b32_e32 v52, 16, v53
	v_and_b32_e32 v53, 0xffff0000, v53
	v_lshlrev_b32_e32 v34, 16, v57
	v_and_b32_e32 v35, 0xffff0000, v57
	v_pk_fma_f32 v[24:25], v[24:25], v[48:49], v[44:45]
	v_pk_fma_f32 v[26:27], v[26:27], v[54:55], v[50:51]
	v_pk_fma_f32 v[28:29], v[28:29], v[66:67], v[64:65]
	v_pk_fma_f32 v[30:31], v[30:31], v[34:35], v[52:53]
	global_store_dwordx4 v[32:33], v[24:27], off nt
	global_store_dwordx4 v[32:33], v[28:31], off offset:16 nt
	global_load_dwordx4 v[24:27], v[58:59], off offset:64
	s_nop 0
	global_load_dwordx4 v[28:31], v[60:61], off offset:64 nt
	v_pk_mul_f32 v[22:23], v[22:23], v[36:37] op_sel_hi:[1,0]
	v_pk_mul_f32 v[20:21], v[20:21], v[36:37] op_sel_hi:[1,0]
	v_pk_mul_f32 v[18:19], v[18:19], v[36:37] op_sel_hi:[1,0]
	v_pk_mul_f32 v[16:17], v[16:17], v[36:37] op_sel_hi:[1,0]
	v_mul_f32_e32 v20, 0xbfb8aa3b, v20
	v_mul_f32_e32 v21, 0xbfb8aa3b, v21
	v_mul_f32_e32 v22, 0xbfb8aa3b, v22
	v_mul_f32_e32 v23, 0xbfb8aa3b, v23
	v_mul_f32_e32 v16, 0xbfb8aa3b, v16
	v_mul_f32_e32 v17, 0xbfb8aa3b, v17
	v_mul_f32_e32 v18, 0xbfb8aa3b, v18
	v_mul_f32_e32 v19, 0xbfb8aa3b, v19
	v_exp_f32_e32 v20, v20
	v_exp_f32_e32 v21, v21
	v_exp_f32_e32 v22, v22
	v_exp_f32_e32 v23, v23
	v_exp_f32_e32 v16, v16
	v_exp_f32_e32 v17, v17
	v_exp_f32_e32 v18, v18
	v_exp_f32_e32 v19, v19
	v_add_f32_e32 v20, 1.0, v20
	v_add_f32_e32 v21, 1.0, v21
	v_add_f32_e32 v22, 1.0, v22
	v_add_f32_e32 v23, 1.0, v23
	v_add_f32_e32 v36, 1.0, v16
	v_add_f32_e32 v37, 1.0, v17
	v_add_f32_e32 v40, 1.0, v18
	v_add_f32_e32 v41, 1.0, v19
	v_rcp_f32_e32 v16, v20
	v_rcp_f32_e32 v17, v21
	v_rcp_f32_e32 v18, v22
	v_rcp_f32_e32 v19, v23
	v_rcp_f32_e32 v20, v36
	v_rcp_f32_e32 v21, v37
	v_rcp_f32_e32 v22, v40
	v_rcp_f32_e32 v23, v41
	v_add_u32_e32 v34, 0xb0, v142
	v_ashrrev_i32_e32 v35, 31, v34
	v_lshlrev_b64 v[38:39], 6, v[34:35]
	v_lshl_add_u64 v[38:39], s[6:7], 0, v[38:39]
	s_waitcnt vmcnt(1)
	v_lshlrev_b32_e32 v36, 16, v24
	v_and_b32_e32 v37, 0xffff0000, v24
	s_waitcnt vmcnt(0)
	v_lshlrev_b32_e32 v40, 16, v28
	v_and_b32_e32 v41, 0xffff0000, v28
	v_lshlrev_b32_e32 v24, 16, v25
	v_and_b32_e32 v25, 0xffff0000, v25
	v_lshlrev_b32_e32 v28, 16, v29
	v_and_b32_e32 v29, 0xffff0000, v29
	v_lshlrev_b32_e32 v42, 16, v26
	v_and_b32_e32 v43, 0xffff0000, v26
	v_lshlrev_b32_e32 v44, 16, v30
	v_and_b32_e32 v45, 0xffff0000, v30
	v_lshlrev_b32_e32 v26, 16, v27
	v_and_b32_e32 v27, 0xffff0000, v27
	v_lshlrev_b32_e32 v30, 16, v31
	v_and_b32_e32 v31, 0xffff0000, v31
	v_pk_fma_f32 v[16:17], v[16:17], v[40:41], v[36:37]
	v_pk_fma_f32 v[18:19], v[18:19], v[28:29], v[24:25]
	v_pk_fma_f32 v[20:21], v[20:21], v[44:45], v[42:43]
	v_pk_fma_f32 v[22:23], v[22:23], v[30:31], v[26:27]
	global_store_dwordx4 v[32:33], v[16:19], off offset:128 nt
	global_store_dwordx4 v[32:33], v[20:23], off offset:144 nt
	global_load_dwordx4 v[16:19], v[38:39], off
	s_nop 0
	global_load_dwordx4 v[20:23], v[38:39], off offset:16
	global_load_dwordx4 v[24:27], v[38:39], off offset:48
	global_load_dwordx4 v[28:31], v[38:39], off offset:32
	v_lshlrev_b64 v[32:33], 10, v[34:35]
	v_lshl_add_u64 v[40:41], v[32:33], 0, v[140:141]
	v_lshlrev_b64 v[36:37], 1, v[40:41]
	v_lshl_add_u64 v[42:43], s[16:17], 0, v[36:37]
	v_lshl_add_u64 v[44:45], s[14:15], 0, v[36:37]
	global_load_dwordx4 v[32:35], v[42:43], off
	global_load_dwordx4 v[36:39], v[44:45], off nt
	v_lshl_add_u64 v[40:41], v[40:41], 2, s[30:31]
	s_waitcnt vmcnt(5)
	v_mov_b32_e32 v46, v17
	v_mov_b32_e32 v47, v18
	v_mov_b32_e32 v17, v19
	s_waitcnt vmcnt(4)
	v_mov_b32_e32 v18, v21
	v_mov_b32_e32 v19, v22
	v_mov_b32_e32 v21, v23
	v_pk_add_f32 v[16:17], v[46:47], v[16:17]
	v_pk_add_f32 v[18:19], v[18:19], v[20:21]
	v_pk_add_f32 v[16:17], v[16:17], v[16:17] op_sel:[0,1] op_sel_hi:[1,0]
	v_pk_add_f32 v[18:19], v[18:19], v[18:19] op_sel:[0,1] op_sel_hi:[1,0]
	s_waitcnt vmcnt(2)
	v_add_f32_e32 v22, v28, v29
	v_add_f32_e32 v28, v30, v31
	v_mov_b32_e32 v23, v26
	v_mov_b32_e32 v29, v27
	v_mov_b32_e32 v17, v24
	v_mov_b32_e32 v19, v25
	v_pk_add_f32 v[20:21], v[22:23], v[28:29]
	v_pk_add_f32 v[16:17], v[16:17], v[18:19]
	s_waitcnt vmcnt(1)
	v_lshlrev_b32_e32 v26, 16, v32
	v_pk_add_f32 v[16:17], v[16:17], v[20:21]
	v_and_b32_e32 v27, 0xffff0000, v32
	v_add_f32_e32 v16, v16, v17
	v_fmamk_f32 v16, v16, 0x3a800000, v150
	v_mul_f32_e32 v17, 0x4b800000, v16
	v_cmp_gt_f32_e32 vcc, s48, v16
	s_waitcnt vmcnt(0)
	v_lshlrev_b32_e32 v30, 16, v36
	v_and_b32_e32 v31, 0xffff0000, v36
	v_cndmask_b32_e32 v16, v16, v17, vcc
	v_rsq_f32_e32 v18, v16
	v_lshlrev_b32_e32 v32, 16, v33
	v_and_b32_e32 v33, 0xffff0000, v33
	v_lshlrev_b32_e32 v36, 16, v37
	v_mul_f32_e32 v19, 0x45800000, v18
	v_cndmask_b32_e32 v18, v18, v19, vcc
	v_pk_mul_f32 v[14:15], v[14:15], v[18:19] op_sel_hi:[1,0]
	v_pk_mul_f32 v[12:13], v[12:13], v[18:19] op_sel_hi:[1,0]
	v_pk_mul_f32 v[10:11], v[10:11], v[18:19] op_sel_hi:[1,0]
	v_pk_mul_f32 v[8:9], v[8:9], v[18:19] op_sel_hi:[1,0]
	v_mul_f32_e32 v12, 0xbfb8aa3b, v12
	v_mul_f32_e32 v13, 0xbfb8aa3b, v13
	v_mul_f32_e32 v14, 0xbfb8aa3b, v14
	v_mul_f32_e32 v15, 0xbfb8aa3b, v15
	v_mul_f32_e32 v8, 0xbfb8aa3b, v8
	v_mul_f32_e32 v9, 0xbfb8aa3b, v9
	v_mul_f32_e32 v10, 0xbfb8aa3b, v10
	v_mul_f32_e32 v11, 0xbfb8aa3b, v11
	v_exp_f32_e32 v12, v12
	v_exp_f32_e32 v13, v13
	v_exp_f32_e32 v14, v14
	v_exp_f32_e32 v15, v15
	v_exp_f32_e32 v8, v8
	v_exp_f32_e32 v9, v9
	v_exp_f32_e32 v10, v10
	v_exp_f32_e32 v11, v11
	v_add_f32_e32 v12, 1.0, v12
	v_add_f32_e32 v13, 1.0, v13
	v_add_f32_e32 v14, 1.0, v14
	v_add_f32_e32 v15, 1.0, v15
	v_add_f32_e32 v19, 1.0, v8
	v_add_f32_e32 v20, 1.0, v9
	v_add_f32_e32 v21, 1.0, v10
	v_add_f32_e32 v22, 1.0, v11
	v_rcp_f32_e32 v8, v12
	v_rcp_f32_e32 v9, v13
	v_rcp_f32_e32 v10, v14
	v_rcp_f32_e32 v11, v15
	v_rcp_f32_e32 v12, v19
	v_rcp_f32_e32 v13, v20
	v_rcp_f32_e32 v14, v21
	v_rcp_f32_e32 v15, v22
	v_and_b32_e32 v37, 0xffff0000, v37
	v_lshlrev_b32_e32 v48, 16, v34
	v_and_b32_e32 v49, 0xffff0000, v34
	v_lshlrev_b32_e32 v50, 16, v38
	v_and_b32_e32 v51, 0xffff0000, v38
	v_lshlrev_b32_e32 v34, 16, v35
	v_and_b32_e32 v35, 0xffff0000, v35
	v_lshlrev_b32_e32 v16, 16, v39
	v_and_b32_e32 v17, 0xffff0000, v39
	v_pk_fma_f32 v[8:9], v[8:9], v[30:31], v[26:27]
	v_pk_fma_f32 v[10:11], v[10:11], v[36:37], v[32:33]
	v_pk_fma_f32 v[12:13], v[12:13], v[50:51], v[48:49]
	v_pk_fma_f32 v[14:15], v[14:15], v[16:17], v[34:35]
	global_store_dwordx4 v[40:41], v[8:11], off nt
	global_store_dwordx4 v[40:41], v[12:15], off offset:16 nt
	global_load_dwordx4 v[8:11], v[42:43], off offset:64
	s_nop 0
	global_load_dwordx4 v[12:15], v[44:45], off offset:64 nt
	v_pk_mul_f32 v[6:7], v[6:7], v[18:19] op_sel_hi:[1,0]
	v_pk_mul_f32 v[4:5], v[4:5], v[18:19] op_sel_hi:[1,0]
	v_pk_mul_f32 v[2:3], v[2:3], v[18:19] op_sel_hi:[1,0]
	v_pk_mul_f32 v[0:1], v[0:1], v[18:19] op_sel_hi:[1,0]
	v_mul_f32_e32 v4, 0xbfb8aa3b, v4
	v_mul_f32_e32 v5, 0xbfb8aa3b, v5
	v_mul_f32_e32 v6, 0xbfb8aa3b, v6
	v_mul_f32_e32 v7, 0xbfb8aa3b, v7
	v_mul_f32_e32 v0, 0xbfb8aa3b, v0
	v_mul_f32_e32 v1, 0xbfb8aa3b, v1
	v_mul_f32_e32 v2, 0xbfb8aa3b, v2
	v_mul_f32_e32 v3, 0xbfb8aa3b, v3
	v_exp_f32_e32 v4, v4
	v_exp_f32_e32 v5, v5
	v_exp_f32_e32 v6, v6
	v_exp_f32_e32 v7, v7
	v_exp_f32_e32 v0, v0
	v_exp_f32_e32 v1, v1
	v_exp_f32_e32 v2, v2
	v_exp_f32_e32 v3, v3
	v_add_f32_e32 v4, 1.0, v4
	v_add_f32_e32 v5, 1.0, v5
	v_add_f32_e32 v6, 1.0, v6
	v_add_f32_e32 v7, 1.0, v7
	v_add_f32_e32 v16, 1.0, v0
	v_add_f32_e32 v17, 1.0, v1
	v_add_f32_e32 v18, 1.0, v2
	v_add_f32_e32 v19, 1.0, v3
	v_rcp_f32_e32 v0, v4
	v_rcp_f32_e32 v1, v5
	v_rcp_f32_e32 v2, v6
	v_rcp_f32_e32 v3, v7
	v_rcp_f32_e32 v4, v16
	v_rcp_f32_e32 v5, v17
	v_rcp_f32_e32 v6, v18
	v_rcp_f32_e32 v7, v19
	s_andn2_b64 vcc, exec, s[0:1]
	s_mov_b64 s[0:1], -1
	s_waitcnt vmcnt(1)
	v_lshlrev_b32_e32 v16, 16, v8
	v_and_b32_e32 v17, 0xffff0000, v8
	s_waitcnt vmcnt(0)
	v_lshlrev_b32_e32 v18, 16, v12
	v_and_b32_e32 v19, 0xffff0000, v12
	v_lshlrev_b32_e32 v8, 16, v9
	v_and_b32_e32 v9, 0xffff0000, v9
	v_lshlrev_b32_e32 v12, 16, v13
	v_and_b32_e32 v13, 0xffff0000, v13
	v_lshlrev_b32_e32 v20, 16, v10
	v_and_b32_e32 v21, 0xffff0000, v10
	v_lshlrev_b32_e32 v22, 16, v14
	v_and_b32_e32 v23, 0xffff0000, v14
	v_lshlrev_b32_e32 v10, 16, v11
	v_and_b32_e32 v11, 0xffff0000, v11
	v_lshlrev_b32_e32 v14, 16, v15
	v_and_b32_e32 v15, 0xffff0000, v15
	v_pk_fma_f32 v[0:1], v[0:1], v[18:19], v[16:17]
	v_pk_fma_f32 v[2:3], v[2:3], v[12:13], v[8:9]
	v_pk_fma_f32 v[4:5], v[4:5], v[22:23], v[20:21]
	v_pk_fma_f32 v[6:7], v[6:7], v[14:15], v[10:11]
	global_store_dwordx4 v[40:41], v[0:3], off offset:128 nt
	global_store_dwordx4 v[40:41], v[4:7], off offset:144 nt
	s_cbranch_vccnz .LBB0_466
	s_andn2_b64 vcc, exec, s[4:5]
	s_cbranch_vccnz .LBB0_465
	s_barrier
	s_branch .LBB0_465
